# seams: non-leaders poll TOPGEN directly (on top of early L1 invalidate)
# baseline (speedup 1.0000x reference)
; __device__ __forceinline__ unsigned xb_ld(unsigned* p)              { return __hip_atomic_load(p, __ATOMIC_RELAXED, __HIP_MEMORY_SCOPE_AGENT); }
; __device__ __forceinline__ unsigned xb_add(unsigned* p, unsigned v) { return __hip_atomic_fetch_add(p, v, __ATOMIC_RELAXED, __HIP_MEMORY_SCOPE_AGENT); }
; #define XB_SPIN(cond, bar) do { unsigned _sp = 0; while (cond) { __builtin_amdgcn_s_sleep(1); \
;     if ((++_sp & 255u) == 0u) { if (xb_ld(&(bar)[XB_TMO])) break; if (_sp > XB_SPIN_CAP) { atomicAdd(&(bar)[XB_TMO], 1u); break; } } } } while (0)
; __device__ __forceinline__ void xcd_barrier(const XcdBarrier& b) {
;     ...
;         const unsigned old = xb_add(&bar[XB_XSUB(b.x)], 1u);
;         const unsigned gen = old / nloc;
;         if (old + 1u == (gen + 1u) * nloc) {
;             __builtin_amdgcn_fence(__ATOMIC_RELEASE, "agent");
;             asm volatile("s_waitcnt vmcnt(0)" ::: "memory");
;             const unsigned og = xb_add(&bar[XB_TOP], 1u);
;             const unsigned tg = og / nx;
;             if (og + 1u == (tg + 1u) * nx) xb_add(&bar[XB_TOPGEN], 1u);
;             else XB_SPIN(xb_ld(&bar[XB_TOPGEN]) == tg, bar);
;             __builtin_amdgcn_fence(__ATOMIC_ACQUIRE, "agent");
;             xb_add(&bar[XB_XGEN(b.x)], 1u);
;             asm volatile("s_waitcnt vmcnt(0)" ::: "memory");
;         } else {
;             XB_SPIN(xb_ld(&bar[XB_XGEN(b.x)]) == gen, bar);
;             __builtin_amdgcn_fence(__ATOMIC_ACQUIRE, "agent");
;             asm volatile("s_waitcnt vmcnt(0)" ::: "memory");
.LBB0_164:
	s_or_b64 exec, exec, s[8:9]
	v_cvt_f32_u32_e32 v4, v2
	s_waitcnt vmcnt(0)
	v_readfirstlane_b32 s3, v3
	v_sub_u32_e32 v3, 0, v2
	v_rcp_iflag_f32_e32 v4, v4
	v_add_u32_e32 v5, s3, v1
	v_mul_f32_e32 v4, 0x4f7ffffe, v4
	v_cvt_u32_f32_e32 v4, v4
	v_mul_lo_u32 v1, v3, v4
	v_mul_hi_u32 v1, v4, v1
	v_add_u32_e32 v1, v4, v1
	v_mul_hi_u32 v1, v5, v1
	v_mul_lo_u32 v3, v1, v2
	v_sub_u32_e32 v3, v5, v3
	v_add_u32_e32 v4, 1, v1
	v_cmp_ge_u32_e32 vcc, v3, v2
	s_nop 1
	v_cndmask_b32_e32 v1, v1, v4, vcc
	v_sub_u32_e32 v4, v3, v2
	v_cndmask_b32_e32 v3, v3, v4, vcc
	v_add_u32_e32 v4, 1, v1
	v_cmp_ge_u32_e32 vcc, v3, v2
	v_add_u32_e32 v3, 1, v5
	s_nop 0
	v_cndmask_b32_e32 v1, v1, v4, vcc
	v_mul_lo_u32 v4, v2, v1
	v_add_u32_e32 v2, v4, v2
	v_cmp_ne_u32_e32 vcc, v3, v2
	s_and_saveexec_b64 s[6:7], vcc
	s_xor_b64 s[6:7], exec, s[6:7]
	s_cbranch_execz .LBB0_178
	s_waitcnt lgkmcnt(0)
	s_add_u32 s24, s54, 0x22a5500
	s_addc_u32 s25, s55, 0
	v_mov_b32_e32 v0, 0
	global_load_dword v0, v0, s[24:25] sc1
	s_waitcnt vmcnt(0)
	v_cmp_eq_u32_e32 vcc, v0, v1
	s_and_saveexec_b64 s[8:9], vcc
	s_cbranch_execz .LBB0_177
	s_add_u32 s14, s54, 0x22a2200
	s_addc_u32 s15, s55, 0
	s_mov_b32 s3, 1
	s_mov_b64 s[26:27], 0
	v_mov_b32_e32 v0, 0
	s_branch .LBB0_168

; __device__ __forceinline__ unsigned xb_ld(unsigned* p)              { return __hip_atomic_load(p, __ATOMIC_RELAXED, __HIP_MEMORY_SCOPE_AGENT); }
; __device__ __forceinline__ unsigned xb_add(unsigned* p, unsigned v) { return __hip_atomic_fetch_add(p, v, __ATOMIC_RELAXED, __HIP_MEMORY_SCOPE_AGENT); }
; #define XB_SPIN(cond, bar) do { unsigned _sp = 0; while (cond) { __builtin_amdgcn_s_sleep(1); \
;     if ((++_sp & 255u) == 0u) { if (xb_ld(&(bar)[XB_TMO])) break; if (_sp > XB_SPIN_CAP) { atomicAdd(&(bar)[XB_TMO], 1u); break; } } } } while (0)
; __device__ __forceinline__ void xcd_barrier(const XcdBarrier& b) {
;     ...
;         const unsigned old = xb_add(&bar[XB_XSUB(b.x)], 1u);
;         const unsigned gen = old / nloc;
;         if (old + 1u == (gen + 1u) * nloc) {
;             __builtin_amdgcn_fence(__ATOMIC_RELEASE, "agent");
;             asm volatile("s_waitcnt vmcnt(0)" ::: "memory");
;             const unsigned og = xb_add(&bar[XB_TOP], 1u);
;             const unsigned tg = og / nx;
;             if (og + 1u == (tg + 1u) * nx) xb_add(&bar[XB_TOPGEN], 1u);
;             else XB_SPIN(xb_ld(&bar[XB_TOPGEN]) == tg, bar);
;             __builtin_amdgcn_fence(__ATOMIC_ACQUIRE, "agent");
;             xb_add(&bar[XB_XGEN(b.x)], 1u);
;             asm volatile("s_waitcnt vmcnt(0)" ::: "memory");
;         } else {
;             XB_SPIN(xb_ld(&bar[XB_XGEN(b.x)]) == gen, bar);
;             __builtin_amdgcn_fence(__ATOMIC_ACQUIRE, "agent");
;             asm volatile("s_waitcnt vmcnt(0)" ::: "memory");
.LBB0_463:
	s_or_b64 exec, exec, s[8:9]
	v_cvt_f32_u32_e32 v4, v2
	s_waitcnt vmcnt(0)
	v_readfirstlane_b32 s3, v3
	v_sub_u32_e32 v3, 0, v2
	v_rcp_iflag_f32_e32 v4, v4
	v_add_u32_e32 v5, s3, v1
	v_mul_f32_e32 v4, 0x4f7ffffe, v4
	v_cvt_u32_f32_e32 v4, v4
	v_mul_lo_u32 v1, v3, v4
	v_mul_hi_u32 v1, v4, v1
	v_add_u32_e32 v1, v4, v1
	v_mul_hi_u32 v1, v5, v1
	v_mul_lo_u32 v3, v1, v2
	v_sub_u32_e32 v3, v5, v3
	v_add_u32_e32 v4, 1, v1
	v_cmp_ge_u32_e32 vcc, v3, v2
	s_nop 1
	v_cndmask_b32_e32 v1, v1, v4, vcc
	v_sub_u32_e32 v4, v3, v2
	v_cndmask_b32_e32 v3, v3, v4, vcc
	v_add_u32_e32 v4, 1, v1
	v_cmp_ge_u32_e32 vcc, v3, v2
	v_add_u32_e32 v3, 1, v5
	s_nop 0
	v_cndmask_b32_e32 v1, v1, v4, vcc
	v_mul_lo_u32 v4, v2, v1
	v_add_u32_e32 v2, v4, v2
	v_cmp_ne_u32_e32 vcc, v3, v2
	s_and_saveexec_b64 s[6:7], vcc
	s_xor_b64 s[6:7], exec, s[6:7]
	s_cbranch_execz .LBB0_477
	s_waitcnt lgkmcnt(0)
	s_add_u32 s24, s54, 0x22a5500
	s_addc_u32 s25, s55, 0
	v_mov_b32_e32 v0, 0
	global_load_dword v0, v0, s[24:25] sc1
	s_waitcnt vmcnt(0)
	v_cmp_eq_u32_e32 vcc, v0, v1
	s_and_saveexec_b64 s[8:9], vcc
	s_cbranch_execz .LBB0_476
	s_add_u32 s10, s54, 0x22a2200
	s_addc_u32 s11, s55, 0
	s_mov_b32 s3, 1
	s_mov_b64 s[26:27], 0
	v_mov_b32_e32 v0, 0
	s_branch .LBB0_467

; __device__ __forceinline__ unsigned xb_ld(unsigned* p)              { return __hip_atomic_load(p, __ATOMIC_RELAXED, __HIP_MEMORY_SCOPE_AGENT); }
; __device__ __forceinline__ unsigned xb_add(unsigned* p, unsigned v) { return __hip_atomic_fetch_add(p, v, __ATOMIC_RELAXED, __HIP_MEMORY_SCOPE_AGENT); }
; #define XB_SPIN(cond, bar) do { unsigned _sp = 0; while (cond) { __builtin_amdgcn_s_sleep(1); \
;     if ((++_sp & 255u) == 0u) { if (xb_ld(&(bar)[XB_TMO])) break; if (_sp > XB_SPIN_CAP) { atomicAdd(&(bar)[XB_TMO], 1u); break; } } } } while (0)
; __device__ __forceinline__ void xcd_barrier(const XcdBarrier& b) {
;     ...
;         const unsigned old = xb_add(&bar[XB_XSUB(b.x)], 1u);
;         const unsigned gen = old / nloc;
;         if (old + 1u == (gen + 1u) * nloc) {
;             __builtin_amdgcn_fence(__ATOMIC_RELEASE, "agent");
;             asm volatile("s_waitcnt vmcnt(0)" ::: "memory");
;             const unsigned og = xb_add(&bar[XB_TOP], 1u);
;             const unsigned tg = og / nx;
;             if (og + 1u == (tg + 1u) * nx) xb_add(&bar[XB_TOPGEN], 1u);
;             else XB_SPIN(xb_ld(&bar[XB_TOPGEN]) == tg, bar);
;             __builtin_amdgcn_fence(__ATOMIC_ACQUIRE, "agent");
;             xb_add(&bar[XB_XGEN(b.x)], 1u);
;             asm volatile("s_waitcnt vmcnt(0)" ::: "memory");
;         } else {
;             XB_SPIN(xb_ld(&bar[XB_XGEN(b.x)]) == gen, bar);
;             __builtin_amdgcn_fence(__ATOMIC_ACQUIRE, "agent");
;             asm volatile("s_waitcnt vmcnt(0)" ::: "memory");
.LBB0_597:
	s_or_b64 exec, exec, s[10:11]
	v_cvt_f32_u32_e32 v4, v2
	s_waitcnt vmcnt(0)
	v_readfirstlane_b32 s3, v3
	v_sub_u32_e32 v3, 0, v2
	v_rcp_iflag_f32_e32 v4, v4
	v_add_u32_e32 v5, s3, v1
	v_mul_f32_e32 v4, 0x4f7ffffe, v4
	v_cvt_u32_f32_e32 v4, v4
	v_mul_lo_u32 v1, v3, v4
	v_mul_hi_u32 v1, v4, v1
	v_add_u32_e32 v1, v4, v1
	v_mul_hi_u32 v1, v5, v1
	v_mul_lo_u32 v3, v1, v2
	v_sub_u32_e32 v3, v5, v3
	v_add_u32_e32 v4, 1, v1
	v_cmp_ge_u32_e32 vcc, v3, v2
	s_nop 1
	v_cndmask_b32_e32 v1, v1, v4, vcc
	v_sub_u32_e32 v4, v3, v2
	v_cndmask_b32_e32 v3, v3, v4, vcc
	v_add_u32_e32 v4, 1, v1
	v_cmp_ge_u32_e32 vcc, v3, v2
	v_add_u32_e32 v3, 1, v5
	s_nop 0
	v_cndmask_b32_e32 v1, v1, v4, vcc
	v_mul_lo_u32 v4, v2, v1
	v_add_u32_e32 v2, v4, v2
	v_cmp_ne_u32_e32 vcc, v3, v2
	s_and_saveexec_b64 s[8:9], vcc
	s_xor_b64 s[8:9], exec, s[8:9]
	s_cbranch_execz .LBB0_611
	s_waitcnt lgkmcnt(0)
	s_add_u32 s24, s54, 0x22a5500
	s_addc_u32 s25, s55, 0
	v_mov_b32_e32 v0, 0
	global_load_dword v0, v0, s[24:25] sc1
	s_waitcnt vmcnt(0)
	v_cmp_eq_u32_e32 vcc, v0, v1
	s_and_saveexec_b64 s[10:11], vcc
	s_cbranch_execz .LBB0_610
	s_add_u32 s14, s54, 0x22a2200
	s_addc_u32 s15, s55, 0
	s_mov_b32 s3, 1
	s_mov_b64 s[26:27], 0
	v_mov_b32_e32 v0, 0
	s_branch .LBB0_601

; __device__ __forceinline__ unsigned xb_ld(unsigned* p)              { return __hip_atomic_load(p, __ATOMIC_RELAXED, __HIP_MEMORY_SCOPE_AGENT); }
; __device__ __forceinline__ unsigned xb_add(unsigned* p, unsigned v) { return __hip_atomic_fetch_add(p, v, __ATOMIC_RELAXED, __HIP_MEMORY_SCOPE_AGENT); }
; #define XB_SPIN(cond, bar) do { unsigned _sp = 0; while (cond) { __builtin_amdgcn_s_sleep(1); \
;     if ((++_sp & 255u) == 0u) { if (xb_ld(&(bar)[XB_TMO])) break; if (_sp > XB_SPIN_CAP) { atomicAdd(&(bar)[XB_TMO], 1u); break; } } } } while (0)
; __device__ __forceinline__ void xcd_barrier(const XcdBarrier& b) {
;     ...
;         const unsigned old = xb_add(&bar[XB_XSUB(b.x)], 1u);
;         const unsigned gen = old / nloc;
;         if (old + 1u == (gen + 1u) * nloc) {
;             __builtin_amdgcn_fence(__ATOMIC_RELEASE, "agent");
;             asm volatile("s_waitcnt vmcnt(0)" ::: "memory");
;             const unsigned og = xb_add(&bar[XB_TOP], 1u);
;             const unsigned tg = og / nx;
;             if (og + 1u == (tg + 1u) * nx) xb_add(&bar[XB_TOPGEN], 1u);
;             else XB_SPIN(xb_ld(&bar[XB_TOPGEN]) == tg, bar);
;             __builtin_amdgcn_fence(__ATOMIC_ACQUIRE, "agent");
;             xb_add(&bar[XB_XGEN(b.x)], 1u);
;             asm volatile("s_waitcnt vmcnt(0)" ::: "memory");
;         } else {
;             XB_SPIN(xb_ld(&bar[XB_XGEN(b.x)]) == gen, bar);
;             __builtin_amdgcn_fence(__ATOMIC_ACQUIRE, "agent");
;             asm volatile("s_waitcnt vmcnt(0)" ::: "memory");
.LBB0_690:
	s_or_b64 exec, exec, s[8:9]
	v_cvt_f32_u32_e32 v4, v2
	s_waitcnt vmcnt(0)
	v_readfirstlane_b32 s3, v3
	v_sub_u32_e32 v3, 0, v2
	v_rcp_iflag_f32_e32 v4, v4
	v_add_u32_e32 v5, s3, v1
	v_mul_f32_e32 v4, 0x4f7ffffe, v4
	v_cvt_u32_f32_e32 v4, v4
	v_mul_lo_u32 v1, v3, v4
	v_mul_hi_u32 v1, v4, v1
	v_add_u32_e32 v1, v4, v1
	v_mul_hi_u32 v1, v5, v1
	v_mul_lo_u32 v3, v1, v2
	v_sub_u32_e32 v3, v5, v3
	v_add_u32_e32 v4, 1, v1
	v_cmp_ge_u32_e32 vcc, v3, v2
	s_nop 1
	v_cndmask_b32_e32 v1, v1, v4, vcc
	v_sub_u32_e32 v4, v3, v2
	v_cndmask_b32_e32 v3, v3, v4, vcc
	v_add_u32_e32 v4, 1, v1
	v_cmp_ge_u32_e32 vcc, v3, v2
	v_add_u32_e32 v3, 1, v5
	s_nop 0
	v_cndmask_b32_e32 v1, v1, v4, vcc
	v_mul_lo_u32 v4, v2, v1
	v_add_u32_e32 v2, v4, v2
	v_cmp_ne_u32_e32 vcc, v3, v2
	s_and_saveexec_b64 s[6:7], vcc
	s_xor_b64 s[6:7], exec, s[6:7]
	s_cbranch_execz .LBB0_704
	s_waitcnt lgkmcnt(0)
	s_add_u32 s20, s54, 0x22a5500
	s_addc_u32 s21, s55, 0
	v_mov_b32_e32 v0, 0
	global_load_dword v0, v0, s[20:21] sc1
	s_waitcnt vmcnt(0)
	v_cmp_eq_u32_e32 vcc, v0, v1
	s_and_saveexec_b64 s[8:9], vcc
	s_cbranch_execz .LBB0_703
	s_add_u32 s10, s54, 0x22a2200
	s_addc_u32 s11, s55, 0
	s_mov_b32 s3, 1
	s_mov_b64 s[24:25], 0
	v_mov_b32_e32 v0, 0
	s_branch .LBB0_694

; __device__ __forceinline__ unsigned xb_ld(unsigned* p)              { return __hip_atomic_load(p, __ATOMIC_RELAXED, __HIP_MEMORY_SCOPE_AGENT); }
; __device__ __forceinline__ unsigned xb_add(unsigned* p, unsigned v) { return __hip_atomic_fetch_add(p, v, __ATOMIC_RELAXED, __HIP_MEMORY_SCOPE_AGENT); }
; #define XB_SPIN(cond, bar) do { unsigned _sp = 0; while (cond) { __builtin_amdgcn_s_sleep(1); \
;     if ((++_sp & 255u) == 0u) { if (xb_ld(&(bar)[XB_TMO])) break; if (_sp > XB_SPIN_CAP) { atomicAdd(&(bar)[XB_TMO], 1u); break; } } } } while (0)
; __device__ __forceinline__ void xcd_barrier(const XcdBarrier& b) {
;     ...
;         const unsigned old = xb_add(&bar[XB_XSUB(b.x)], 1u);
;         const unsigned gen = old / nloc;
;         if (old + 1u == (gen + 1u) * nloc) {
;             __builtin_amdgcn_fence(__ATOMIC_RELEASE, "agent");
;             asm volatile("s_waitcnt vmcnt(0)" ::: "memory");
;             const unsigned og = xb_add(&bar[XB_TOP], 1u);
;             const unsigned tg = og / nx;
;             if (og + 1u == (tg + 1u) * nx) xb_add(&bar[XB_TOPGEN], 1u);
;             else XB_SPIN(xb_ld(&bar[XB_TOPGEN]) == tg, bar);
;             __builtin_amdgcn_fence(__ATOMIC_ACQUIRE, "agent");
;             xb_add(&bar[XB_XGEN(b.x)], 1u);
;             asm volatile("s_waitcnt vmcnt(0)" ::: "memory");
;         } else {
;             XB_SPIN(xb_ld(&bar[XB_XGEN(b.x)]) == gen, bar);
;             __builtin_amdgcn_fence(__ATOMIC_ACQUIRE, "agent");
;             asm volatile("s_waitcnt vmcnt(0)" ::: "memory");
.LBB0_765:
	s_or_b64 exec, exec, s[8:9]
	v_cvt_f32_u32_e32 v4, v2
	s_waitcnt vmcnt(0)
	v_readfirstlane_b32 s3, v3
	v_sub_u32_e32 v3, 0, v2
	v_rcp_iflag_f32_e32 v4, v4
	v_add_u32_e32 v5, s3, v1
	v_mul_f32_e32 v4, 0x4f7ffffe, v4
	v_cvt_u32_f32_e32 v4, v4
	v_mul_lo_u32 v1, v3, v4
	v_mul_hi_u32 v1, v4, v1
	v_add_u32_e32 v1, v4, v1
	v_mul_hi_u32 v1, v5, v1
	v_mul_lo_u32 v3, v1, v2
	v_sub_u32_e32 v3, v5, v3
	v_add_u32_e32 v4, 1, v1
	v_cmp_ge_u32_e32 vcc, v3, v2
	s_nop 1
	v_cndmask_b32_e32 v1, v1, v4, vcc
	v_sub_u32_e32 v4, v3, v2
	v_cndmask_b32_e32 v3, v3, v4, vcc
	v_add_u32_e32 v4, 1, v1
	v_cmp_ge_u32_e32 vcc, v3, v2
	v_add_u32_e32 v3, 1, v5
	s_nop 0
	v_cndmask_b32_e32 v1, v1, v4, vcc
	v_mul_lo_u32 v4, v2, v1
	v_add_u32_e32 v2, v4, v2
	v_cmp_ne_u32_e32 vcc, v3, v2
	s_and_saveexec_b64 s[6:7], vcc
	s_xor_b64 s[6:7], exec, s[6:7]
	s_cbranch_execz .LBB0_779
	s_waitcnt lgkmcnt(0)
	s_add_u32 s14, s54, 0x22a5500
	s_addc_u32 s15, s55, 0
	v_mov_b32_e32 v0, 0
	global_load_dword v0, v0, s[14:15] sc1
	s_waitcnt vmcnt(0)
	v_cmp_eq_u32_e32 vcc, v0, v1
	s_and_saveexec_b64 s[8:9], vcc
	s_cbranch_execz .LBB0_778
	s_add_u32 s10, s54, 0x22a2200
	s_addc_u32 s11, s55, 0
	s_mov_b32 s3, 1
	s_mov_b64 s[16:17], 0
	v_mov_b32_e32 v0, 0
	s_branch .LBB0_769

; __device__ __forceinline__ unsigned xb_ld(unsigned* p)              { return __hip_atomic_load(p, __ATOMIC_RELAXED, __HIP_MEMORY_SCOPE_AGENT); }
; __device__ __forceinline__ unsigned xb_add(unsigned* p, unsigned v) { return __hip_atomic_fetch_add(p, v, __ATOMIC_RELAXED, __HIP_MEMORY_SCOPE_AGENT); }
; #define XB_SPIN(cond, bar) do { unsigned _sp = 0; while (cond) { __builtin_amdgcn_s_sleep(1); \
;     if ((++_sp & 255u) == 0u) { if (xb_ld(&(bar)[XB_TMO])) break; if (_sp > XB_SPIN_CAP) { atomicAdd(&(bar)[XB_TMO], 1u); break; } } } } while (0)
; __device__ __forceinline__ void xcd_barrier(const XcdBarrier& b) {
;     ...
;         const unsigned old = xb_add(&bar[XB_XSUB(b.x)], 1u);
;         const unsigned gen = old / nloc;
;         if (old + 1u == (gen + 1u) * nloc) {
;             __builtin_amdgcn_fence(__ATOMIC_RELEASE, "agent");
;             asm volatile("s_waitcnt vmcnt(0)" ::: "memory");
;             const unsigned og = xb_add(&bar[XB_TOP], 1u);
;             const unsigned tg = og / nx;
;             if (og + 1u == (tg + 1u) * nx) xb_add(&bar[XB_TOPGEN], 1u);
;             else XB_SPIN(xb_ld(&bar[XB_TOPGEN]) == tg, bar);
;             __builtin_amdgcn_fence(__ATOMIC_ACQUIRE, "agent");
;             xb_add(&bar[XB_XGEN(b.x)], 1u);
;             asm volatile("s_waitcnt vmcnt(0)" ::: "memory");
;         } else {
;             XB_SPIN(xb_ld(&bar[XB_XGEN(b.x)]) == gen, bar);
;             __builtin_amdgcn_fence(__ATOMIC_ACQUIRE, "agent");
;             asm volatile("s_waitcnt vmcnt(0)" ::: "memory");
.LBB0_861:
	s_or_b64 exec, exec, s[10:11]
	v_cvt_f32_u32_e32 v4, v2
	s_waitcnt vmcnt(0)
	v_readfirstlane_b32 s3, v3
	v_sub_u32_e32 v3, 0, v2
	v_rcp_iflag_f32_e32 v4, v4
	v_add_u32_e32 v5, s3, v1
	v_mul_f32_e32 v4, 0x4f7ffffe, v4
	v_cvt_u32_f32_e32 v4, v4
	v_mul_lo_u32 v1, v3, v4
	v_mul_hi_u32 v1, v4, v1
	v_add_u32_e32 v1, v4, v1
	v_mul_hi_u32 v1, v5, v1
	v_mul_lo_u32 v3, v1, v2
	v_sub_u32_e32 v3, v5, v3
	v_add_u32_e32 v4, 1, v1
	v_cmp_ge_u32_e32 vcc, v3, v2
	s_nop 1
	v_cndmask_b32_e32 v1, v1, v4, vcc
	v_sub_u32_e32 v4, v3, v2
	v_cndmask_b32_e32 v3, v3, v4, vcc
	v_add_u32_e32 v4, 1, v1
	v_cmp_ge_u32_e32 vcc, v3, v2
	v_add_u32_e32 v3, 1, v5
	s_nop 0
	v_cndmask_b32_e32 v1, v1, v4, vcc
	v_mul_lo_u32 v4, v2, v1
	v_add_u32_e32 v2, v4, v2
	v_cmp_ne_u32_e32 vcc, v3, v2
	s_and_saveexec_b64 s[8:9], vcc
	s_xor_b64 s[8:9], exec, s[8:9]
	s_cbranch_execz .LBB0_875
	s_waitcnt lgkmcnt(0)
	s_add_u32 s16, s54, 0x22a5500
	s_addc_u32 s17, s55, 0
	v_mov_b32_e32 v0, 0
	global_load_dword v0, v0, s[16:17] sc1
	s_waitcnt vmcnt(0)
	v_cmp_eq_u32_e32 vcc, v0, v1
	s_and_saveexec_b64 s[10:11], vcc
	s_cbranch_execz .LBB0_874
	s_add_u32 s14, s54, 0x22a2200
	s_addc_u32 s15, s55, 0
	s_mov_b32 s3, 1
	s_mov_b64 s[18:19], 0
	v_mov_b32_e32 v0, 0
	s_branch .LBB0_865

; __device__ __forceinline__ unsigned xb_ld(unsigned* p)              { return __hip_atomic_load(p, __ATOMIC_RELAXED, __HIP_MEMORY_SCOPE_AGENT); }
; __device__ __forceinline__ unsigned xb_add(unsigned* p, unsigned v) { return __hip_atomic_fetch_add(p, v, __ATOMIC_RELAXED, __HIP_MEMORY_SCOPE_AGENT); }
; #define XB_SPIN(cond, bar) do { unsigned _sp = 0; while (cond) { __builtin_amdgcn_s_sleep(1); \
;     if ((++_sp & 255u) == 0u) { if (xb_ld(&(bar)[XB_TMO])) break; if (_sp > XB_SPIN_CAP) { atomicAdd(&(bar)[XB_TMO], 1u); break; } } } } while (0)
; __device__ __forceinline__ void xcd_barrier(const XcdBarrier& b) {
;     ...
;         const unsigned old = xb_add(&bar[XB_XSUB(b.x)], 1u);
;         const unsigned gen = old / nloc;
;         if (old + 1u == (gen + 1u) * nloc) {
;             __builtin_amdgcn_fence(__ATOMIC_RELEASE, "agent");
;             asm volatile("s_waitcnt vmcnt(0)" ::: "memory");
;             const unsigned og = xb_add(&bar[XB_TOP], 1u);
;             const unsigned tg = og / nx;
;             if (og + 1u == (tg + 1u) * nx) xb_add(&bar[XB_TOPGEN], 1u);
;             else XB_SPIN(xb_ld(&bar[XB_TOPGEN]) == tg, bar);
;             __builtin_amdgcn_fence(__ATOMIC_ACQUIRE, "agent");
;             xb_add(&bar[XB_XGEN(b.x)], 1u);
;             asm volatile("s_waitcnt vmcnt(0)" ::: "memory");
;         } else {
;             XB_SPIN(xb_ld(&bar[XB_XGEN(b.x)]) == gen, bar);
;             __builtin_amdgcn_fence(__ATOMIC_ACQUIRE, "agent");
;             asm volatile("s_waitcnt vmcnt(0)" ::: "memory");
.LBB0_1230:
	s_or_b64 exec, exec, s[8:9]
	v_cvt_f32_u32_e32 v4, v2
	s_waitcnt vmcnt(0)
	v_readfirstlane_b32 s3, v3
	v_sub_u32_e32 v3, 0, v2
	v_rcp_iflag_f32_e32 v4, v4
	v_add_u32_e32 v5, s3, v1
	v_mul_f32_e32 v4, 0x4f7ffffe, v4
	v_cvt_u32_f32_e32 v4, v4
	v_mul_lo_u32 v1, v3, v4
	v_mul_hi_u32 v1, v4, v1
	v_add_u32_e32 v1, v4, v1
	v_mul_hi_u32 v1, v5, v1
	v_mul_lo_u32 v3, v1, v2
	v_sub_u32_e32 v3, v5, v3
	v_add_u32_e32 v4, 1, v1
	v_cmp_ge_u32_e32 vcc, v3, v2
	s_nop 1
	v_cndmask_b32_e32 v1, v1, v4, vcc
	v_sub_u32_e32 v4, v3, v2
	v_cndmask_b32_e32 v3, v3, v4, vcc
	v_add_u32_e32 v4, 1, v1
	v_cmp_ge_u32_e32 vcc, v3, v2
	v_add_u32_e32 v3, 1, v5
	s_nop 0
	v_cndmask_b32_e32 v1, v1, v4, vcc
	v_mul_lo_u32 v4, v2, v1
	v_add_u32_e32 v2, v4, v2
	v_cmp_ne_u32_e32 vcc, v3, v2
	s_and_saveexec_b64 s[6:7], vcc
	s_xor_b64 s[6:7], exec, s[6:7]
	s_cbranch_execz .LBB0_1244
	s_waitcnt lgkmcnt(0)
	s_add_u32 s16, s54, 0x22a5500
	s_addc_u32 s17, s55, 0
	v_mov_b32_e32 v0, 0
	global_load_dword v0, v0, s[16:17] sc1
	s_waitcnt vmcnt(0)
	v_cmp_eq_u32_e32 vcc, v0, v1
	s_and_saveexec_b64 s[8:9], vcc
	s_cbranch_execz .LBB0_1243
	s_add_u32 s14, s54, 0x22a2200
	s_addc_u32 s15, s55, 0
	s_mov_b32 s3, 1
	s_mov_b64 s[18:19], 0
	v_mov_b32_e32 v0, 0
	s_branch .LBB0_1234
